# SEL radix-select: broadcast of selected bin via v_readlane instead of 3 ds_bpermute
# baseline (speedup 1.0000x reference)
; DI void select_item(const P& p, int b, int quad4, int bid, char* smem, const SelPre& pre) {
;     ...
;       const unsigned long long fb = __ballot(found);
;       const int fl = fb ? (__ffsll((long long)fb) - 1) : 0;
;       const unsigned dsel = __shfl(dig, fl), nneed = __shfl(need - above, fl), ncnt = __shfl(cnt, fl);
;       prefix |= dsel << shift; pmask |= 0xffu << shift; need = nneed; eq_total = ncnt;
.LBB0_475:
	s_or_b64 exec, exec, s[20:21]
	v_cndmask_b32_e64 v0, 0, 1, s[18:19]
	v_cmp_ne_u32_e32 vcc, 0, v0
	s_ff1_i32_b64 s18, vcc
	s_cmp_lg_u64 vcc, 0
	s_cselect_b32 s18, s18, 0
	v_sub_u32_e32 v2, v6, v18
	v_readlane_b32 vcc_lo, v24, s18
	v_readlane_b32 s19, v25, s18
	v_readlane_b32 vcc_hi, v2, s18
	s_nop 1
	v_mov_b32_e32 v1, vcc_lo
	v_mov_b32_e32 v6, vcc_hi
	v_mov_b32_e32 v18, s19
	s_lshl_b32 s18, 0xff, s31
	v_lshl_or_b32 v9, v1, s31, v9
	s_or_b32 s60, s18, s60
	s_mov_b64 s[20:21], 0
	s_and_b64 vcc, exec, s[6:7]
	s_cbranch_vccnz .LBB0_477
	s_mov_b32 s31, 0
	s_branch .LBB0_462
